# prep phase: dependent-load loops in ada-modulation (silu table) and hyena-filter weight staging replaced by batched loads (all loads in flight, same arithmetic)
# speedup vs baseline: 1.0780x; 1.0123x over previous
.LBB0_814:
	s_and_b64 vcc, exec, s[0:1]
	s_cbranch_vccz .LBB0_879
	s_sub_i32 s12, 0x111, s15
	v_mov_b32_e32 v46, v175
	s_lshr_b32 s13, s14, 7
	s_lshr_b32 s11, s12, 7
	v_lshlrev_b32_e32 v0, 2, v46
	v_readlane_b32 s56, v251, 46
	v_readlane_b32 s57, v251, 47
	v_readlane_b32 s58, v251, 48
	v_readlane_b32 s59, v251, 49
	v_readlane_b32 s60, v251, 50
	v_readlane_b32 s61, v251, 51
	v_readlane_b32 s62, v251, 52
	v_readlane_b32 s63, v251, 53
	v_readlane_b32 s64, v251, 54
	v_readlane_b32 s65, v251, 55
	v_readlane_b32 s66, v251, 56
	v_readlane_b32 s67, v251, 57
	v_readlane_b32 s68, v251, 58
	v_readlane_b32 s69, v251, 59
	v_readlane_b32 s70, v251, 60
	v_readlane_b32 s71, v251, 61
	s_mul_i32 s4, s11, 0x1100
	s_add_u32 s4, s68, s4
	s_addc_u32 s5, s69, 0
	global_load_dword v8, v0, s[4:5]
	global_load_dword v9, v0, s[4:5] offset:1024
	global_load_dword v10, v0, s[4:5] offset:2048
	global_load_dword v11, v0, s[4:5] offset:3072
	s_lshl_b32 s6, s11, 14
	s_add_u32 s6, s36, s6
	s_addc_u32 s7, s37, 0
	v_add_u32_e32 v2, 0x1000, v0
	v_add_u32_e32 v3, 0x2000, v0
	v_add_u32_e32 v4, 0x3000, v0
	global_load_dword v12, v0, s[6:7]
	global_load_dword v13, v0, s[6:7] offset:1024
	global_load_dword v14, v0, s[6:7] offset:2048
	global_load_dword v15, v0, s[6:7] offset:3072
	global_load_dword v16, v2, s[6:7]
	global_load_dword v17, v2, s[6:7] offset:1024
	global_load_dword v18, v2, s[6:7] offset:2048
	global_load_dword v19, v2, s[6:7] offset:3072
	global_load_dword v20, v3, s[6:7]
	global_load_dword v21, v3, s[6:7] offset:1024
	global_load_dword v22, v3, s[6:7] offset:2048
	global_load_dword v23, v3, s[6:7] offset:3072
	global_load_dword v24, v4, s[6:7]
	global_load_dword v25, v4, s[6:7] offset:1024
	global_load_dword v26, v4, s[6:7] offset:2048
	global_load_dword v27, v4, s[6:7] offset:3072
	v_cmp_gt_i32_e32 vcc, 64, v46
	s_and_saveexec_b64 s[0:1], vcc
	s_cbranch_execz .Lfst_a
	v_lshl_add_u32 v5, s11, 6, v46
	v_lshlrev_b32_e32 v5, 2, v5
	global_load_dword v28, v5, s[70:71]
	global_load_dword v29, v5, s[38:39]
	global_load_dword v30, v2, s[4:5]
.Lfst_a:
	s_or_b64 exec, exec, s[0:1]
	s_movk_i32 s8, 0x80
	v_cmp_gt_i32_e32 vcc, s8, v46
	s_and_saveexec_b64 s[0:1], vcc
	s_cbranch_execz .Lfst_b
	s_and_b32 s8, s12, 0x180
	v_add_u32_e32 v6, s8, v46
	v_lshlrev_b32_e32 v6, 2, v6
	global_load_dword v31, v6, s[42:43]
.Lfst_b:
	s_or_b64 exec, exec, s[0:1]
	s_waitcnt vmcnt(0)
	v_add_u32_e32 v7, 0x2000, v0
	ds_write_b32 v7, v8
	ds_write_b32 v7, v9 offset:1024
	ds_write_b32 v7, v10 offset:2048
	ds_write_b32 v7, v11 offset:3072
	v_readlane_b32 s8, v252, 2
	s_nop 1
	v_add_u32_e32 v6, s8, v0
	ds_write_b32 v6, v12
	ds_write_b32 v6, v13 offset:1024
	ds_write_b32 v6, v14 offset:2048
	ds_write_b32 v6, v15 offset:3072
	ds_write_b32 v6, v16 offset:4096
	ds_write_b32 v6, v17 offset:5120
	ds_write_b32 v6, v18 offset:6144
	ds_write_b32 v6, v19 offset:7168
	ds_write_b32 v6, v20 offset:8192
	ds_write_b32 v6, v21 offset:9216
	ds_write_b32 v6, v22 offset:10240
	ds_write_b32 v6, v23 offset:11264
	ds_write_b32 v6, v24 offset:12288
	ds_write_b32 v6, v25 offset:13312
	ds_write_b32 v6, v26 offset:14336
	ds_write_b32 v6, v27 offset:15360
	v_cmp_gt_i32_e32 vcc, 64, v46
	s_and_saveexec_b64 s[0:1], vcc
	s_cbranch_execz .Lfst_c
	ds_write_b32 v7, v30 offset:4096
	ds_write2st64_b32 v0, v28, v29 offset0:113 offset1:114
.Lfst_c:
	s_or_b64 exec, exec, s[0:1]
	s_movk_i32 s8, 0x80
	v_cmp_gt_i32_e32 vcc, s8, v46
	s_and_saveexec_b64 s[0:1], vcc
	s_cbranch_execz .Lfst_d
	ds_write_b32 v0, v31 offset:29440
.Lfst_d:
.LBB0_839:
	s_or_b64 exec, exec, s[0:1]
	s_lshl_b32 s0, s10, 4
	v_ashrrev_i32_e32 v47, 4, v46
	s_and_b32 s6, s0, 0x7f0
	v_add_u32_e32 v2, s6, v47
	v_cvt_f32_i32_e32 v2, v2
	s_mov_b32 s4, 0x44ffe000
	v_lshlrev_b32_e32 v0, 2, v0
	v_and_b32_e32 v95, 0xf0, v0
	v_div_scale_f32 v3, s[0:1], s4, s4, v2
	v_rcp_f32_e32 v4, v3
	v_add_u32_e32 v0, 0, v95
	s_waitcnt lgkmcnt(0)
	s_barrier
	v_fma_f32 v5, -v3, v4, 1.0
	v_fmac_f32_e32 v4, v5, v4
	v_div_scale_f32 v5, vcc, v2, s4, v2
	v_mul_f32_e32 v6, v5, v4
	v_fma_f32 v7, -v3, v6, v5
	v_fmac_f32_e32 v6, v7, v4
	v_fma_f32 v3, -v3, v6, v5
	v_div_fmas_f32 v3, v3, v4, v6
	v_div_fixup_f32 v80, v3, s4, v2
	v_mul_f32_e32 v2, 0x40c90fdb, v2
	v_mul_f32_e32 v2, 0x3a000000, v2
	v_mul_f32_e32 v3, 0x38d1b717, v2
	v_mul_f32_e32 v4, 0.15915494, v3
	v_rndne_f32_e32 v4, v4
	v_fmac_f32_e32 v3, 0xc0c90fdb, v4
	v_fmac_f32_e32 v3, 0x343bbd2e, v4
	v_mul_f32_e32 v3, 0.15915494, v3
	v_sin_f32_e32 v81, v3
	v_cos_f32_e32 v82, v3
	v_mul_f32_e32 v3, 0x3f8002cf, v2
	v_mul_f32_e32 v4, 0.15915494, v3
	v_rndne_f32_e32 v4, v4
	v_fmac_f32_e32 v3, 0xc0c90fdb, v4
	v_fmac_f32_e32 v3, 0x343bbd2e, v4
	v_mul_f32_e32 v3, 0.15915494, v3
	v_sin_f32_e32 v83, v3
	v_cos_f32_e32 v84, v3
	v_mul_f32_e32 v3, 0x4000012b, v2
	v_mul_f32_e32 v4, 0.15915494, v3
	v_rndne_f32_e32 v4, v4
	v_fmac_f32_e32 v3, 0xc0c90fdb, v4
	v_fmac_f32_e32 v3, 0x343bbd2e, v4
	v_mul_f32_e32 v3, 0.15915494, v3
	v_sin_f32_e32 v85, v3
	v_cos_f32_e32 v86, v3
	v_mul_f32_e32 v3, 0x404000ef, v2
	v_mul_f32_e32 v4, 0.15915494, v3
	v_rndne_f32_e32 v4, v4
	v_fmac_f32_e32 v3, 0xc0c90fdb, v4
	v_fmac_f32_e32 v3, 0x343bbd2e, v4
	v_mul_f32_e32 v3, 0.15915494, v3
	v_sin_f32_e32 v87, v3
	v_cos_f32_e32 v88, v3
	v_mul_f32_e32 v3, 0x4080005a, v2
	v_mul_f32_e32 v4, 0.15915494, v3
	v_rndne_f32_e32 v4, v4
	v_fmac_f32_e32 v3, 0xc0c90fdb, v4
	v_fmac_f32_e32 v3, 0x343bbd2e, v4
	v_mul_f32_e32 v3, 0.15915494, v3
	v_sin_f32_e32 v89, v3
	v_cos_f32_e32 v90, v3
	v_mul_f32_e32 v3, 0x40a0003c, v2
	v_mul_f32_e32 v4, 0.15915494, v3
	v_rndne_f32_e32 v4, v4
	v_fmac_f32_e32 v3, 0xc0c90fdb, v4
	v_fmac_f32_e32 v3, 0x343bbd2e, v4
	v_mul_f32_e32 v3, 0.15915494, v3
	v_sin_f32_e32 v91, v3
	v_cos_f32_e32 v92, v3
	v_mul_f32_e32 v3, 0x40c0001e, v2
	v_mul_f32_e32 v4, 0.15915494, v3
	v_rndne_f32_e32 v4, v4
	v_fmac_f32_e32 v3, 0xc0c90fdb, v4
	v_fmac_f32_e32 v3, 0x343bbd2e, v4
	v_mul_f32_e32 v3, 0.15915494, v3
	v_mul_f32_e32 v2, 0x40e00000, v2
	v_sin_f32_e32 v93, v3
	v_cos_f32_e32 v94, v3
	v_mul_f32_e32 v3, 0.15915494, v2
	v_rndne_f32_e32 v3, v3
	v_fmac_f32_e32 v2, 0xc0c90fdb, v3
	v_fmac_f32_e32 v2, 0x343bbd2e, v3
	v_mul_f32_e32 v14, 0.15915494, v2
	ds_read_b128 v[2:5], v0 offset:28928
	ds_read_b128 v[6:9], v0 offset:8192
	ds_read_b128 v[10:13], v0 offset:8448
	ds_read_b128 v[18:21], v0 offset:8704
	v_sin_f32_e32 v96, v14
	v_cos_f32_e32 v97, v14
	ds_read_b128 v[14:17], v0 offset:12288
	s_waitcnt lgkmcnt(3)
	v_fma_f32 v2, v80, v6, v2
	ds_read_b128 v[22:25], v0 offset:8960
	ds_read_b128 v[26:29], v0 offset:9216
	ds_read_b128 v[30:33], v0 offset:9472
	s_waitcnt lgkmcnt(5)
	v_fmac_f32_e32 v2, v82, v10
	ds_read_b128 v[34:37], v0 offset:9728
	ds_read_b128 v[38:41], v0 offset:9984
	s_waitcnt lgkmcnt(6)
	v_fmac_f32_e32 v2, v84, v18
	s_waitcnt lgkmcnt(4)
	v_fmac_f32_e32 v2, v86, v22
	v_fma_f32 v3, v80, v7, v3
	s_waitcnt lgkmcnt(3)
	v_fmac_f32_e32 v2, v88, v26
	v_fmac_f32_e32 v3, v82, v11
	s_waitcnt lgkmcnt(2)
	v_fmac_f32_e32 v2, v90, v30
	ds_read_b128 v[42:45], v0 offset:10240
	ds_read_b128 v[48:51], v0 offset:10496
	ds_read_b128 v[52:55], v0 offset:10752
	v_fmac_f32_e32 v3, v84, v19
	s_waitcnt lgkmcnt(4)
	v_fmac_f32_e32 v2, v92, v34
	ds_read_b128 v[56:59], v0 offset:11008
	ds_read_b128 v[60:63], v0 offset:11264
	v_fmac_f32_e32 v3, v86, v23
	v_fma_f32 v4, v80, v8, v4
	s_waitcnt lgkmcnt(5)
	v_fmac_f32_e32 v2, v94, v38
	v_fmac_f32_e32 v3, v88, v27
	v_fmac_f32_e32 v4, v82, v12
	s_waitcnt lgkmcnt(4)
	v_fmac_f32_e32 v2, v97, v42
	v_fmac_f32_e32 v3, v90, v31
	v_fmac_f32_e32 v4, v84, v20
	s_waitcnt lgkmcnt(3)
	v_fma_f32 v2, -v81, v48, v2
	v_fmac_f32_e32 v3, v92, v35
	v_fmac_f32_e32 v4, v86, v24
	v_fmac_f32_e32 v5, v80, v9
	s_waitcnt lgkmcnt(2)
	v_fma_f32 v2, -v83, v52, v2
	ds_read_b128 v[64:67], v0 offset:11520
	s_waitcnt vmcnt(20)
	ds_read_b128 v[68:71], v0 offset:11776
	ds_read_b128 v[72:75], v0 offset:12032
	v_fmac_f32_e32 v3, v94, v39
	v_fmac_f32_e32 v4, v88, v28
	v_fmac_f32_e32 v5, v82, v13
	s_waitcnt lgkmcnt(4)
	v_fma_f32 v2, -v85, v56, v2
	v_fmac_f32_e32 v3, v97, v43
	v_fmac_f32_e32 v4, v90, v32
	v_fmac_f32_e32 v5, v84, v21
	s_waitcnt lgkmcnt(3)
	v_fma_f32 v2, -v87, v60, v2
	ds_read_b128 v[76:79], v0 offset:29440
	v_fma_f32 v3, -v81, v49, v3
	v_fmac_f32_e32 v4, v92, v36
	v_fmac_f32_e32 v5, v86, v25
	s_waitcnt lgkmcnt(3)
	v_fma_f32 v2, -v89, v64, v2
	v_fma_f32 v3, -v83, v53, v3
	v_fmac_f32_e32 v4, v94, v40
	v_fmac_f32_e32 v5, v88, v29
	s_waitcnt lgkmcnt(2)
	v_fma_f32 v2, -v91, v68, v2
	v_fma_f32 v3, -v85, v57, v3
	v_fmac_f32_e32 v4, v97, v44
	v_fmac_f32_e32 v5, v90, v33
	s_waitcnt lgkmcnt(1)
	v_fma_f32 v2, -v93, v72, v2
	v_fma_f32 v3, -v87, v61, v3
	v_fma_f32 v4, -v81, v50, v4
	v_fmac_f32_e32 v5, v92, v37
	v_fma_f32 v2, -v96, v14, v2
	v_fma_f32 v3, -v89, v65, v3
	v_fma_f32 v4, -v83, v54, v4
	v_fmac_f32_e32 v5, v94, v41
	s_waitcnt lgkmcnt(0)
	v_mul_f32_e32 v2, v76, v2
	v_fma_f32 v3, -v91, v69, v3
	v_fma_f32 v4, -v85, v58, v4
	v_fmac_f32_e32 v5, v97, v45
	v_mul_f32_e32 v6, 0.15915494, v2
	v_fma_f32 v3, -v93, v73, v3
	v_fma_f32 v4, -v87, v62, v4
	v_fma_f32 v5, -v81, v51, v5
	v_rndne_f32_e32 v6, v6
	v_fma_f32 v3, -v96, v15, v3
	v_fma_f32 v4, -v89, v66, v4
	v_fma_f32 v5, -v83, v55, v5
	v_fmac_f32_e32 v2, 0xc0c90fdb, v6
	v_mul_f32_e32 v3, v77, v3
	v_fma_f32 v4, -v91, v70, v4
	v_fma_f32 v5, -v85, v59, v5
	v_fmac_f32_e32 v2, 0x343bbd2e, v6
	v_mul_f32_e32 v6, 0.15915494, v3
	v_fma_f32 v4, -v93, v74, v4
	v_fma_f32 v5, -v87, v63, v5
	v_rndne_f32_e32 v6, v6
	v_fma_f32 v4, -v96, v16, v4
	v_fma_f32 v5, -v89, v67, v5
	v_fmac_f32_e32 v3, 0xc0c90fdb, v6
	v_mul_f32_e32 v4, v78, v4
	v_fma_f32 v5, -v91, v71, v5
	v_fmac_f32_e32 v3, 0x343bbd2e, v6
	v_mul_f32_e32 v6, 0.15915494, v4
	v_fma_f32 v5, -v93, v75, v5
	v_rndne_f32_e32 v6, v6
	v_fma_f32 v5, -v96, v17, v5
	v_fmac_f32_e32 v4, 0xc0c90fdb, v6
	v_mul_f32_e32 v5, v79, v5
	v_fmac_f32_e32 v4, 0x343bbd2e, v6
	v_mul_f32_e32 v6, 0.15915494, v5
	v_rndne_f32_e32 v6, v6
	v_fmac_f32_e32 v5, 0xc0c90fdb, v6
	v_fmac_f32_e32 v5, 0x343bbd2e, v6
	v_mul_f32_e32 v2, 0.15915494, v2
	v_mul_f32_e32 v3, 0.15915494, v3
	v_mul_f32_e32 v4, 0.15915494, v4
	v_mul_f32_e32 v5, 0.15915494, v5
	v_sin_f32_e32 v2, v2
	v_sin_f32_e32 v3, v3
	v_sin_f32_e32 v4, v4
	v_sin_f32_e32 v5, v5
	v_lshl_add_u32 v7, v47, 8, 0
	v_add_u32_e32 v6, v7, v95
	v_and_b32_e32 v8, 15, v46
	ds_write_b128 v6, v[2:5]
	s_waitcnt lgkmcnt(0)
	s_barrier
	ds_read_b128 v[2:5], v0 offset:29184
	v_readlane_b32 s0, v252, 2
	s_nop 1
	v_lshl_add_u32 v8, v8, 4, s0
	s_mov_b32 s0, 0

.LBB0_847:
	v_mov_b32_e32 v14, v175
	s_movk_i32 s0, 0x2400
	s_nop 0
	v_cmp_gt_i32_e32 vcc, s0, v14
	s_and_saveexec_b64 s[0:1], vcc
	v_readlane_b32 s56, v252, 7
	s_mov_b64 s[8:9], 0x400
	v_readlane_b32 s58, v252, 9
	v_readlane_b32 s59, v252, 10
	v_readlane_b32 s62, v252, 13
	v_readlane_b32 s63, v252, 14
	v_readlane_b32 s57, v252, 8
	v_readlane_b32 s60, v252, 11
	v_readlane_b32 s61, v252, 12
	v_readlane_b32 s64, v252, 15
	v_readlane_b32 s65, v252, 16
	v_readlane_b32 s66, v252, 17
	v_readlane_b32 s67, v252, 18
	v_readlane_b32 s68, v252, 19
	v_readlane_b32 s69, v252, 20
	v_readlane_b32 s70, v252, 21
	v_readlane_b32 s71, v252, 22
	s_cbranch_execz .LBB0_850
	v_lshl_add_u32 v4, v14, 2, 0
	v_lshlrev_b32_e32 v2, 2, v14
	global_load_dword v16, v2, s[58:59]
	global_load_dword v17, v2, s[58:59] offset:1024
	global_load_dword v18, v2, s[58:59] offset:2048
	global_load_dword v19, v2, s[58:59] offset:3072
	v_add_u32_e32 v3, 0x1000, v2
	global_load_dword v20, v3, s[58:59]
	global_load_dword v21, v3, s[58:59] offset:1024
	global_load_dword v22, v3, s[58:59] offset:2048
	global_load_dword v23, v3, s[58:59] offset:3072
	v_add_u32_e32 v3, 0x2000, v2
	global_load_dword v24, v3, s[58:59]
	global_load_dword v25, v3, s[58:59] offset:1024
	global_load_dword v26, v3, s[58:59] offset:2048
	global_load_dword v27, v3, s[58:59] offset:3072
	v_add_u32_e32 v3, 0x3000, v2
	global_load_dword v28, v3, s[58:59]
	global_load_dword v29, v3, s[58:59] offset:1024
	global_load_dword v30, v3, s[58:59] offset:2048
	global_load_dword v31, v3, s[58:59] offset:3072
	v_add_u32_e32 v3, 0x4000, v2
	global_load_dword v32, v3, s[58:59]
	global_load_dword v33, v3, s[58:59] offset:1024
	global_load_dword v34, v3, s[58:59] offset:2048
	global_load_dword v35, v3, s[58:59] offset:3072
	v_add_u32_e32 v3, 0x5000, v2
	global_load_dword v36, v3, s[58:59]
	global_load_dword v37, v3, s[58:59] offset:1024
	global_load_dword v38, v3, s[58:59] offset:2048
	global_load_dword v39, v3, s[58:59] offset:3072
	v_add_u32_e32 v3, 0x6000, v2
	global_load_dword v40, v3, s[58:59]
	global_load_dword v41, v3, s[58:59] offset:1024
	global_load_dword v42, v3, s[58:59] offset:2048
	global_load_dword v43, v3, s[58:59] offset:3072
	v_add_u32_e32 v3, 0x7000, v2
	global_load_dword v44, v3, s[58:59]
	global_load_dword v45, v3, s[58:59] offset:1024
	global_load_dword v46, v3, s[58:59] offset:2048
	global_load_dword v47, v3, s[58:59] offset:3072
	global_load_dword v48, v2, s[62:63]
	global_load_dword v49, v2, s[62:63] offset:1024
	global_load_dword v50, v2, s[62:63] offset:2048
	global_load_dword v51, v2, s[62:63] offset:3072
	s_waitcnt vmcnt(35)
	v_mul_f32_e32 v6, 0xbfb8aa3b, v16
	v_exp_f32_e32 v6, v6
	s_nop 0
	v_add_f32_e32 v6, 1.0, v6
	v_div_scale_f32 v7, s[6:7], v6, v6, v16
	v_rcp_f32_e32 v8, v7
	v_div_scale_f32 v9, vcc, v16, v6, v16
	v_fma_f32 v10, -v7, v8, 1.0
	v_fmac_f32_e32 v8, v10, v8
	v_mul_f32_e32 v10, v9, v8
	v_fma_f32 v11, -v7, v10, v9
	v_fmac_f32_e32 v10, v11, v8
	v_fma_f32 v7, -v7, v10, v9
	v_div_fmas_f32 v7, v7, v8, v10
	v_div_fixup_f32 v0, v7, v6, v16
	ds_write_b32 v4, v0
	s_waitcnt vmcnt(34)
	v_mul_f32_e32 v6, 0xbfb8aa3b, v17
	v_exp_f32_e32 v6, v6
	s_nop 0
	v_add_f32_e32 v6, 1.0, v6
	v_div_scale_f32 v7, s[6:7], v6, v6, v17
	v_rcp_f32_e32 v8, v7
	v_div_scale_f32 v9, vcc, v17, v6, v17
	v_fma_f32 v10, -v7, v8, 1.0
	v_fmac_f32_e32 v8, v10, v8
	v_mul_f32_e32 v10, v9, v8
	v_fma_f32 v11, -v7, v10, v9
	v_fmac_f32_e32 v10, v11, v8
	v_fma_f32 v7, -v7, v10, v9
	v_div_fmas_f32 v7, v7, v8, v10
	v_div_fixup_f32 v0, v7, v6, v17
	ds_write_b32 v4, v0 offset:1024
	s_waitcnt vmcnt(33)
	v_mul_f32_e32 v6, 0xbfb8aa3b, v18
	v_exp_f32_e32 v6, v6
	s_nop 0
	v_add_f32_e32 v6, 1.0, v6
	v_div_scale_f32 v7, s[6:7], v6, v6, v18
	v_rcp_f32_e32 v8, v7
	v_div_scale_f32 v9, vcc, v18, v6, v18
	v_fma_f32 v10, -v7, v8, 1.0
	v_fmac_f32_e32 v8, v10, v8
	v_mul_f32_e32 v10, v9, v8
	v_fma_f32 v11, -v7, v10, v9
	v_fmac_f32_e32 v10, v11, v8
	v_fma_f32 v7, -v7, v10, v9
	v_div_fmas_f32 v7, v7, v8, v10
	v_div_fixup_f32 v0, v7, v6, v18
	ds_write_b32 v4, v0 offset:2048
	s_waitcnt vmcnt(32)
	v_mul_f32_e32 v6, 0xbfb8aa3b, v19
	v_exp_f32_e32 v6, v6
	s_nop 0
	v_add_f32_e32 v6, 1.0, v6
	v_div_scale_f32 v7, s[6:7], v6, v6, v19
	v_rcp_f32_e32 v8, v7
	v_div_scale_f32 v9, vcc, v19, v6, v19
	v_fma_f32 v10, -v7, v8, 1.0
	v_fmac_f32_e32 v8, v10, v8
	v_mul_f32_e32 v10, v9, v8
	v_fma_f32 v11, -v7, v10, v9
	v_fmac_f32_e32 v10, v11, v8
	v_fma_f32 v7, -v7, v10, v9
	v_div_fmas_f32 v7, v7, v8, v10
	v_div_fixup_f32 v0, v7, v6, v19
	ds_write_b32 v4, v0 offset:3072
	s_waitcnt vmcnt(31)
	v_mul_f32_e32 v6, 0xbfb8aa3b, v20
	v_exp_f32_e32 v6, v6
	s_nop 0
	v_add_f32_e32 v6, 1.0, v6
	v_div_scale_f32 v7, s[6:7], v6, v6, v20
	v_rcp_f32_e32 v8, v7
	v_div_scale_f32 v9, vcc, v20, v6, v20
	v_fma_f32 v10, -v7, v8, 1.0
	v_fmac_f32_e32 v8, v10, v8
	v_mul_f32_e32 v10, v9, v8
	v_fma_f32 v11, -v7, v10, v9
	v_fmac_f32_e32 v10, v11, v8
	v_fma_f32 v7, -v7, v10, v9
	v_div_fmas_f32 v7, v7, v8, v10
	v_div_fixup_f32 v0, v7, v6, v20
	ds_write_b32 v4, v0 offset:4096
	s_waitcnt vmcnt(30)
	v_mul_f32_e32 v6, 0xbfb8aa3b, v21
	v_exp_f32_e32 v6, v6
	s_nop 0
	v_add_f32_e32 v6, 1.0, v6
	v_div_scale_f32 v7, s[6:7], v6, v6, v21
	v_rcp_f32_e32 v8, v7
	v_div_scale_f32 v9, vcc, v21, v6, v21
	v_fma_f32 v10, -v7, v8, 1.0
	v_fmac_f32_e32 v8, v10, v8
	v_mul_f32_e32 v10, v9, v8
	v_fma_f32 v11, -v7, v10, v9
	v_fmac_f32_e32 v10, v11, v8
	v_fma_f32 v7, -v7, v10, v9
	v_div_fmas_f32 v7, v7, v8, v10
	v_div_fixup_f32 v0, v7, v6, v21
	ds_write_b32 v4, v0 offset:5120
	s_waitcnt vmcnt(29)
	v_mul_f32_e32 v6, 0xbfb8aa3b, v22
	v_exp_f32_e32 v6, v6
	s_nop 0
	v_add_f32_e32 v6, 1.0, v6
	v_div_scale_f32 v7, s[6:7], v6, v6, v22
	v_rcp_f32_e32 v8, v7
	v_div_scale_f32 v9, vcc, v22, v6, v22
	v_fma_f32 v10, -v7, v8, 1.0
	v_fmac_f32_e32 v8, v10, v8
	v_mul_f32_e32 v10, v9, v8
	v_fma_f32 v11, -v7, v10, v9
	v_fmac_f32_e32 v10, v11, v8
	v_fma_f32 v7, -v7, v10, v9
	v_div_fmas_f32 v7, v7, v8, v10
	v_div_fixup_f32 v0, v7, v6, v22
	ds_write_b32 v4, v0 offset:6144
	s_waitcnt vmcnt(28)
	v_mul_f32_e32 v6, 0xbfb8aa3b, v23
	v_exp_f32_e32 v6, v6
	s_nop 0
	v_add_f32_e32 v6, 1.0, v6
	v_div_scale_f32 v7, s[6:7], v6, v6, v23
	v_rcp_f32_e32 v8, v7
	v_div_scale_f32 v9, vcc, v23, v6, v23
	v_fma_f32 v10, -v7, v8, 1.0
	v_fmac_f32_e32 v8, v10, v8
	v_mul_f32_e32 v10, v9, v8
	v_fma_f32 v11, -v7, v10, v9
	v_fmac_f32_e32 v10, v11, v8
	v_fma_f32 v7, -v7, v10, v9
	v_div_fmas_f32 v7, v7, v8, v10
	v_div_fixup_f32 v0, v7, v6, v23
	ds_write_b32 v4, v0 offset:7168
	s_waitcnt vmcnt(27)
	v_mul_f32_e32 v6, 0xbfb8aa3b, v24
	v_exp_f32_e32 v6, v6
	s_nop 0
	v_add_f32_e32 v6, 1.0, v6
	v_div_scale_f32 v7, s[6:7], v6, v6, v24
	v_rcp_f32_e32 v8, v7
	v_div_scale_f32 v9, vcc, v24, v6, v24
	v_fma_f32 v10, -v7, v8, 1.0
	v_fmac_f32_e32 v8, v10, v8
	v_mul_f32_e32 v10, v9, v8
	v_fma_f32 v11, -v7, v10, v9
	v_fmac_f32_e32 v10, v11, v8
	v_fma_f32 v7, -v7, v10, v9
	v_div_fmas_f32 v7, v7, v8, v10
	v_div_fixup_f32 v0, v7, v6, v24
	ds_write_b32 v4, v0 offset:8192
	s_waitcnt vmcnt(26)
	v_mul_f32_e32 v6, 0xbfb8aa3b, v25
	v_exp_f32_e32 v6, v6
	s_nop 0
	v_add_f32_e32 v6, 1.0, v6
	v_div_scale_f32 v7, s[6:7], v6, v6, v25
	v_rcp_f32_e32 v8, v7
	v_div_scale_f32 v9, vcc, v25, v6, v25
	v_fma_f32 v10, -v7, v8, 1.0
	v_fmac_f32_e32 v8, v10, v8
	v_mul_f32_e32 v10, v9, v8
	v_fma_f32 v11, -v7, v10, v9
	v_fmac_f32_e32 v10, v11, v8
	v_fma_f32 v7, -v7, v10, v9
	v_div_fmas_f32 v7, v7, v8, v10
	v_div_fixup_f32 v0, v7, v6, v25
	ds_write_b32 v4, v0 offset:9216
	s_waitcnt vmcnt(25)
	v_mul_f32_e32 v6, 0xbfb8aa3b, v26
	v_exp_f32_e32 v6, v6
	s_nop 0
	v_add_f32_e32 v6, 1.0, v6
	v_div_scale_f32 v7, s[6:7], v6, v6, v26
	v_rcp_f32_e32 v8, v7
	v_div_scale_f32 v9, vcc, v26, v6, v26
	v_fma_f32 v10, -v7, v8, 1.0
	v_fmac_f32_e32 v8, v10, v8
	v_mul_f32_e32 v10, v9, v8
	v_fma_f32 v11, -v7, v10, v9
	v_fmac_f32_e32 v10, v11, v8
	v_fma_f32 v7, -v7, v10, v9
	v_div_fmas_f32 v7, v7, v8, v10
	v_div_fixup_f32 v0, v7, v6, v26
	ds_write_b32 v4, v0 offset:10240
	s_waitcnt vmcnt(24)
	v_mul_f32_e32 v6, 0xbfb8aa3b, v27
	v_exp_f32_e32 v6, v6
	s_nop 0
	v_add_f32_e32 v6, 1.0, v6
	v_div_scale_f32 v7, s[6:7], v6, v6, v27
	v_rcp_f32_e32 v8, v7
	v_div_scale_f32 v9, vcc, v27, v6, v27
	v_fma_f32 v10, -v7, v8, 1.0
	v_fmac_f32_e32 v8, v10, v8
	v_mul_f32_e32 v10, v9, v8
	v_fma_f32 v11, -v7, v10, v9
	v_fmac_f32_e32 v10, v11, v8
	v_fma_f32 v7, -v7, v10, v9
	v_div_fmas_f32 v7, v7, v8, v10
	v_div_fixup_f32 v0, v7, v6, v27
	ds_write_b32 v4, v0 offset:11264
	s_waitcnt vmcnt(23)
	v_mul_f32_e32 v6, 0xbfb8aa3b, v28
	v_exp_f32_e32 v6, v6
	s_nop 0
	v_add_f32_e32 v6, 1.0, v6
	v_div_scale_f32 v7, s[6:7], v6, v6, v28
	v_rcp_f32_e32 v8, v7
	v_div_scale_f32 v9, vcc, v28, v6, v28
	v_fma_f32 v10, -v7, v8, 1.0
	v_fmac_f32_e32 v8, v10, v8
	v_mul_f32_e32 v10, v9, v8
	v_fma_f32 v11, -v7, v10, v9
	v_fmac_f32_e32 v10, v11, v8
	v_fma_f32 v7, -v7, v10, v9
	v_div_fmas_f32 v7, v7, v8, v10
	v_div_fixup_f32 v0, v7, v6, v28
	ds_write_b32 v4, v0 offset:12288
	s_waitcnt vmcnt(22)
	v_mul_f32_e32 v6, 0xbfb8aa3b, v29
	v_exp_f32_e32 v6, v6
	s_nop 0
	v_add_f32_e32 v6, 1.0, v6
	v_div_scale_f32 v7, s[6:7], v6, v6, v29
	v_rcp_f32_e32 v8, v7
	v_div_scale_f32 v9, vcc, v29, v6, v29
	v_fma_f32 v10, -v7, v8, 1.0
	v_fmac_f32_e32 v8, v10, v8
	v_mul_f32_e32 v10, v9, v8
	v_fma_f32 v11, -v7, v10, v9
	v_fmac_f32_e32 v10, v11, v8
	v_fma_f32 v7, -v7, v10, v9
	v_div_fmas_f32 v7, v7, v8, v10
	v_div_fixup_f32 v0, v7, v6, v29
	ds_write_b32 v4, v0 offset:13312
	s_waitcnt vmcnt(21)
	v_mul_f32_e32 v6, 0xbfb8aa3b, v30
	v_exp_f32_e32 v6, v6
	s_nop 0
	v_add_f32_e32 v6, 1.0, v6
	v_div_scale_f32 v7, s[6:7], v6, v6, v30
	v_rcp_f32_e32 v8, v7
	v_div_scale_f32 v9, vcc, v30, v6, v30
	v_fma_f32 v10, -v7, v8, 1.0
	v_fmac_f32_e32 v8, v10, v8
	v_mul_f32_e32 v10, v9, v8
	v_fma_f32 v11, -v7, v10, v9
	v_fmac_f32_e32 v10, v11, v8
	v_fma_f32 v7, -v7, v10, v9
	v_div_fmas_f32 v7, v7, v8, v10
	v_div_fixup_f32 v0, v7, v6, v30
	ds_write_b32 v4, v0 offset:14336
	s_waitcnt vmcnt(20)
	v_mul_f32_e32 v6, 0xbfb8aa3b, v31
	v_exp_f32_e32 v6, v6
	s_nop 0
	v_add_f32_e32 v6, 1.0, v6
	v_div_scale_f32 v7, s[6:7], v6, v6, v31
	v_rcp_f32_e32 v8, v7
	v_div_scale_f32 v9, vcc, v31, v6, v31
	v_fma_f32 v10, -v7, v8, 1.0
	v_fmac_f32_e32 v8, v10, v8
	v_mul_f32_e32 v10, v9, v8
	v_fma_f32 v11, -v7, v10, v9
	v_fmac_f32_e32 v10, v11, v8
	v_fma_f32 v7, -v7, v10, v9
	v_div_fmas_f32 v7, v7, v8, v10
	v_div_fixup_f32 v0, v7, v6, v31
	ds_write_b32 v4, v0 offset:15360
	s_waitcnt vmcnt(19)
	v_mul_f32_e32 v6, 0xbfb8aa3b, v32
	v_exp_f32_e32 v6, v6
	s_nop 0
	v_add_f32_e32 v6, 1.0, v6
	v_div_scale_f32 v7, s[6:7], v6, v6, v32
	v_rcp_f32_e32 v8, v7
	v_div_scale_f32 v9, vcc, v32, v6, v32
	v_fma_f32 v10, -v7, v8, 1.0
	v_fmac_f32_e32 v8, v10, v8
	v_mul_f32_e32 v10, v9, v8
	v_fma_f32 v11, -v7, v10, v9
	v_fmac_f32_e32 v10, v11, v8
	v_fma_f32 v7, -v7, v10, v9
	v_div_fmas_f32 v7, v7, v8, v10
	v_div_fixup_f32 v0, v7, v6, v32
	ds_write_b32 v4, v0 offset:16384
	s_waitcnt vmcnt(18)
	v_mul_f32_e32 v6, 0xbfb8aa3b, v33
	v_exp_f32_e32 v6, v6
	s_nop 0
	v_add_f32_e32 v6, 1.0, v6
	v_div_scale_f32 v7, s[6:7], v6, v6, v33
	v_rcp_f32_e32 v8, v7
	v_div_scale_f32 v9, vcc, v33, v6, v33
	v_fma_f32 v10, -v7, v8, 1.0
	v_fmac_f32_e32 v8, v10, v8
	v_mul_f32_e32 v10, v9, v8
	v_fma_f32 v11, -v7, v10, v9
	v_fmac_f32_e32 v10, v11, v8
	v_fma_f32 v7, -v7, v10, v9
	v_div_fmas_f32 v7, v7, v8, v10
	v_div_fixup_f32 v0, v7, v6, v33
	ds_write_b32 v4, v0 offset:17408
	s_waitcnt vmcnt(17)
	v_mul_f32_e32 v6, 0xbfb8aa3b, v34
	v_exp_f32_e32 v6, v6
	s_nop 0
	v_add_f32_e32 v6, 1.0, v6
	v_div_scale_f32 v7, s[6:7], v6, v6, v34
	v_rcp_f32_e32 v8, v7
	v_div_scale_f32 v9, vcc, v34, v6, v34
	v_fma_f32 v10, -v7, v8, 1.0
	v_fmac_f32_e32 v8, v10, v8
	v_mul_f32_e32 v10, v9, v8
	v_fma_f32 v11, -v7, v10, v9
	v_fmac_f32_e32 v10, v11, v8
	v_fma_f32 v7, -v7, v10, v9
	v_div_fmas_f32 v7, v7, v8, v10
	v_div_fixup_f32 v0, v7, v6, v34
	ds_write_b32 v4, v0 offset:18432
	s_waitcnt vmcnt(16)
	v_mul_f32_e32 v6, 0xbfb8aa3b, v35
	v_exp_f32_e32 v6, v6
	s_nop 0
	v_add_f32_e32 v6, 1.0, v6
	v_div_scale_f32 v7, s[6:7], v6, v6, v35
	v_rcp_f32_e32 v8, v7
	v_div_scale_f32 v9, vcc, v35, v6, v35
	v_fma_f32 v10, -v7, v8, 1.0
	v_fmac_f32_e32 v8, v10, v8
	v_mul_f32_e32 v10, v9, v8
	v_fma_f32 v11, -v7, v10, v9
	v_fmac_f32_e32 v10, v11, v8
	v_fma_f32 v7, -v7, v10, v9
	v_div_fmas_f32 v7, v7, v8, v10
	v_div_fixup_f32 v0, v7, v6, v35
	ds_write_b32 v4, v0 offset:19456
	s_waitcnt vmcnt(15)
	v_mul_f32_e32 v6, 0xbfb8aa3b, v36
	v_exp_f32_e32 v6, v6
	s_nop 0
	v_add_f32_e32 v6, 1.0, v6
	v_div_scale_f32 v7, s[6:7], v6, v6, v36
	v_rcp_f32_e32 v8, v7
	v_div_scale_f32 v9, vcc, v36, v6, v36
	v_fma_f32 v10, -v7, v8, 1.0
	v_fmac_f32_e32 v8, v10, v8
	v_mul_f32_e32 v10, v9, v8
	v_fma_f32 v11, -v7, v10, v9
	v_fmac_f32_e32 v10, v11, v8
	v_fma_f32 v7, -v7, v10, v9
	v_div_fmas_f32 v7, v7, v8, v10
	v_div_fixup_f32 v0, v7, v6, v36
	ds_write_b32 v4, v0 offset:20480
	s_waitcnt vmcnt(14)
	v_mul_f32_e32 v6, 0xbfb8aa3b, v37
	v_exp_f32_e32 v6, v6
	s_nop 0
	v_add_f32_e32 v6, 1.0, v6
	v_div_scale_f32 v7, s[6:7], v6, v6, v37
	v_rcp_f32_e32 v8, v7
	v_div_scale_f32 v9, vcc, v37, v6, v37
	v_fma_f32 v10, -v7, v8, 1.0
	v_fmac_f32_e32 v8, v10, v8
	v_mul_f32_e32 v10, v9, v8
	v_fma_f32 v11, -v7, v10, v9
	v_fmac_f32_e32 v10, v11, v8
	v_fma_f32 v7, -v7, v10, v9
	v_div_fmas_f32 v7, v7, v8, v10
	v_div_fixup_f32 v0, v7, v6, v37
	ds_write_b32 v4, v0 offset:21504
	s_waitcnt vmcnt(13)
	v_mul_f32_e32 v6, 0xbfb8aa3b, v38
	v_exp_f32_e32 v6, v6
	s_nop 0
	v_add_f32_e32 v6, 1.0, v6
	v_div_scale_f32 v7, s[6:7], v6, v6, v38
	v_rcp_f32_e32 v8, v7
	v_div_scale_f32 v9, vcc, v38, v6, v38
	v_fma_f32 v10, -v7, v8, 1.0
	v_fmac_f32_e32 v8, v10, v8
	v_mul_f32_e32 v10, v9, v8
	v_fma_f32 v11, -v7, v10, v9
	v_fmac_f32_e32 v10, v11, v8
	v_fma_f32 v7, -v7, v10, v9
	v_div_fmas_f32 v7, v7, v8, v10
	v_div_fixup_f32 v0, v7, v6, v38
	ds_write_b32 v4, v0 offset:22528
	s_waitcnt vmcnt(12)
	v_mul_f32_e32 v6, 0xbfb8aa3b, v39
	v_exp_f32_e32 v6, v6
	s_nop 0
	v_add_f32_e32 v6, 1.0, v6
	v_div_scale_f32 v7, s[6:7], v6, v6, v39
	v_rcp_f32_e32 v8, v7
	v_div_scale_f32 v9, vcc, v39, v6, v39
	v_fma_f32 v10, -v7, v8, 1.0
	v_fmac_f32_e32 v8, v10, v8
	v_mul_f32_e32 v10, v9, v8
	v_fma_f32 v11, -v7, v10, v9
	v_fmac_f32_e32 v10, v11, v8
	v_fma_f32 v7, -v7, v10, v9
	v_div_fmas_f32 v7, v7, v8, v10
	v_div_fixup_f32 v0, v7, v6, v39
	ds_write_b32 v4, v0 offset:23552
	s_waitcnt vmcnt(11)
	v_mul_f32_e32 v6, 0xbfb8aa3b, v40
	v_exp_f32_e32 v6, v6
	s_nop 0
	v_add_f32_e32 v6, 1.0, v6
	v_div_scale_f32 v7, s[6:7], v6, v6, v40
	v_rcp_f32_e32 v8, v7
	v_div_scale_f32 v9, vcc, v40, v6, v40
	v_fma_f32 v10, -v7, v8, 1.0
	v_fmac_f32_e32 v8, v10, v8
	v_mul_f32_e32 v10, v9, v8
	v_fma_f32 v11, -v7, v10, v9
	v_fmac_f32_e32 v10, v11, v8
	v_fma_f32 v7, -v7, v10, v9
	v_div_fmas_f32 v7, v7, v8, v10
	v_div_fixup_f32 v0, v7, v6, v40
	ds_write_b32 v4, v0 offset:24576
	s_waitcnt vmcnt(10)
	v_mul_f32_e32 v6, 0xbfb8aa3b, v41
	v_exp_f32_e32 v6, v6
	s_nop 0
	v_add_f32_e32 v6, 1.0, v6
	v_div_scale_f32 v7, s[6:7], v6, v6, v41
	v_rcp_f32_e32 v8, v7
	v_div_scale_f32 v9, vcc, v41, v6, v41
	v_fma_f32 v10, -v7, v8, 1.0
	v_fmac_f32_e32 v8, v10, v8
	v_mul_f32_e32 v10, v9, v8
	v_fma_f32 v11, -v7, v10, v9
	v_fmac_f32_e32 v10, v11, v8
	v_fma_f32 v7, -v7, v10, v9
	v_div_fmas_f32 v7, v7, v8, v10
	v_div_fixup_f32 v0, v7, v6, v41
	ds_write_b32 v4, v0 offset:25600
	s_waitcnt vmcnt(9)
	v_mul_f32_e32 v6, 0xbfb8aa3b, v42
	v_exp_f32_e32 v6, v6
	s_nop 0
	v_add_f32_e32 v6, 1.0, v6
	v_div_scale_f32 v7, s[6:7], v6, v6, v42
	v_rcp_f32_e32 v8, v7
	v_div_scale_f32 v9, vcc, v42, v6, v42
	v_fma_f32 v10, -v7, v8, 1.0
	v_fmac_f32_e32 v8, v10, v8
	v_mul_f32_e32 v10, v9, v8
	v_fma_f32 v11, -v7, v10, v9
	v_fmac_f32_e32 v10, v11, v8
	v_fma_f32 v7, -v7, v10, v9
	v_div_fmas_f32 v7, v7, v8, v10
	v_div_fixup_f32 v0, v7, v6, v42
	ds_write_b32 v4, v0 offset:26624
	s_waitcnt vmcnt(8)
	v_mul_f32_e32 v6, 0xbfb8aa3b, v43
	v_exp_f32_e32 v6, v6
	s_nop 0
	v_add_f32_e32 v6, 1.0, v6
	v_div_scale_f32 v7, s[6:7], v6, v6, v43
	v_rcp_f32_e32 v8, v7
	v_div_scale_f32 v9, vcc, v43, v6, v43
	v_fma_f32 v10, -v7, v8, 1.0
	v_fmac_f32_e32 v8, v10, v8
	v_mul_f32_e32 v10, v9, v8
	v_fma_f32 v11, -v7, v10, v9
	v_fmac_f32_e32 v10, v11, v8
	v_fma_f32 v7, -v7, v10, v9
	v_div_fmas_f32 v7, v7, v8, v10
	v_div_fixup_f32 v0, v7, v6, v43
	ds_write_b32 v4, v0 offset:27648
	s_waitcnt vmcnt(7)
	v_mul_f32_e32 v6, 0xbfb8aa3b, v44
	v_exp_f32_e32 v6, v6
	s_nop 0
	v_add_f32_e32 v6, 1.0, v6
	v_div_scale_f32 v7, s[6:7], v6, v6, v44
	v_rcp_f32_e32 v8, v7
	v_div_scale_f32 v9, vcc, v44, v6, v44
	v_fma_f32 v10, -v7, v8, 1.0
	v_fmac_f32_e32 v8, v10, v8
	v_mul_f32_e32 v10, v9, v8
	v_fma_f32 v11, -v7, v10, v9
	v_fmac_f32_e32 v10, v11, v8
	v_fma_f32 v7, -v7, v10, v9
	v_div_fmas_f32 v7, v7, v8, v10
	v_div_fixup_f32 v0, v7, v6, v44
	ds_write_b32 v4, v0 offset:28672
	s_waitcnt vmcnt(6)
	v_mul_f32_e32 v6, 0xbfb8aa3b, v45
	v_exp_f32_e32 v6, v6
	s_nop 0
	v_add_f32_e32 v6, 1.0, v6
	v_div_scale_f32 v7, s[6:7], v6, v6, v45
	v_rcp_f32_e32 v8, v7
	v_div_scale_f32 v9, vcc, v45, v6, v45
	v_fma_f32 v10, -v7, v8, 1.0
	v_fmac_f32_e32 v8, v10, v8
	v_mul_f32_e32 v10, v9, v8
	v_fma_f32 v11, -v7, v10, v9
	v_fmac_f32_e32 v10, v11, v8
	v_fma_f32 v7, -v7, v10, v9
	v_div_fmas_f32 v7, v7, v8, v10
	v_div_fixup_f32 v0, v7, v6, v45
	ds_write_b32 v4, v0 offset:29696
	s_waitcnt vmcnt(5)
	v_mul_f32_e32 v6, 0xbfb8aa3b, v46
	v_exp_f32_e32 v6, v6
	s_nop 0
	v_add_f32_e32 v6, 1.0, v6
	v_div_scale_f32 v7, s[6:7], v6, v6, v46
	v_rcp_f32_e32 v8, v7
	v_div_scale_f32 v9, vcc, v46, v6, v46
	v_fma_f32 v10, -v7, v8, 1.0
	v_fmac_f32_e32 v8, v10, v8
	v_mul_f32_e32 v10, v9, v8
	v_fma_f32 v11, -v7, v10, v9
	v_fmac_f32_e32 v10, v11, v8
	v_fma_f32 v7, -v7, v10, v9
	v_div_fmas_f32 v7, v7, v8, v10
	v_div_fixup_f32 v0, v7, v6, v46
	ds_write_b32 v4, v0 offset:30720
	s_waitcnt vmcnt(4)
	v_mul_f32_e32 v6, 0xbfb8aa3b, v47
	v_exp_f32_e32 v6, v6
	s_nop 0
	v_add_f32_e32 v6, 1.0, v6
	v_div_scale_f32 v7, s[6:7], v6, v6, v47
	v_rcp_f32_e32 v8, v7
	v_div_scale_f32 v9, vcc, v47, v6, v47
	v_fma_f32 v10, -v7, v8, 1.0
	v_fmac_f32_e32 v8, v10, v8
	v_mul_f32_e32 v10, v9, v8
	v_fma_f32 v11, -v7, v10, v9
	v_fmac_f32_e32 v10, v11, v8
	v_fma_f32 v7, -v7, v10, v9
	v_div_fmas_f32 v7, v7, v8, v10
	v_div_fixup_f32 v0, v7, v6, v47
	ds_write_b32 v4, v0 offset:31744
	s_waitcnt vmcnt(3)
	v_mul_f32_e32 v6, 0xbfb8aa3b, v48
	v_exp_f32_e32 v6, v6
	s_nop 0
	v_add_f32_e32 v6, 1.0, v6
	v_div_scale_f32 v7, s[6:7], v6, v6, v48
	v_rcp_f32_e32 v8, v7
	v_div_scale_f32 v9, vcc, v48, v6, v48
	v_fma_f32 v10, -v7, v8, 1.0
	v_fmac_f32_e32 v8, v10, v8
	v_mul_f32_e32 v10, v9, v8
	v_fma_f32 v11, -v7, v10, v9
	v_fmac_f32_e32 v10, v11, v8
	v_fma_f32 v7, -v7, v10, v9
	v_div_fmas_f32 v7, v7, v8, v10
	v_div_fixup_f32 v0, v7, v6, v48
	ds_write_b32 v4, v0 offset:32768
	s_waitcnt vmcnt(2)
	v_mul_f32_e32 v6, 0xbfb8aa3b, v49
	v_exp_f32_e32 v6, v6
	s_nop 0
	v_add_f32_e32 v6, 1.0, v6
	v_div_scale_f32 v7, s[6:7], v6, v6, v49
	v_rcp_f32_e32 v8, v7
	v_div_scale_f32 v9, vcc, v49, v6, v49
	v_fma_f32 v10, -v7, v8, 1.0
	v_fmac_f32_e32 v8, v10, v8
	v_mul_f32_e32 v10, v9, v8
	v_fma_f32 v11, -v7, v10, v9
	v_fmac_f32_e32 v10, v11, v8
	v_fma_f32 v7, -v7, v10, v9
	v_div_fmas_f32 v7, v7, v8, v10
	v_div_fixup_f32 v0, v7, v6, v49
	ds_write_b32 v4, v0 offset:33792
	s_waitcnt vmcnt(1)
	v_mul_f32_e32 v6, 0xbfb8aa3b, v50
	v_exp_f32_e32 v6, v6
	s_nop 0
	v_add_f32_e32 v6, 1.0, v6
	v_div_scale_f32 v7, s[6:7], v6, v6, v50
	v_rcp_f32_e32 v8, v7
	v_div_scale_f32 v9, vcc, v50, v6, v50
	v_fma_f32 v10, -v7, v8, 1.0
	v_fmac_f32_e32 v8, v10, v8
	v_mul_f32_e32 v10, v9, v8
	v_fma_f32 v11, -v7, v10, v9
	v_fmac_f32_e32 v10, v11, v8
	v_fma_f32 v7, -v7, v10, v9
	v_div_fmas_f32 v7, v7, v8, v10
	v_div_fixup_f32 v0, v7, v6, v50
	ds_write_b32 v4, v0 offset:34816
	s_waitcnt vmcnt(0)
	v_mul_f32_e32 v6, 0xbfb8aa3b, v51
	v_exp_f32_e32 v6, v6
	s_nop 0
	v_add_f32_e32 v6, 1.0, v6
	v_div_scale_f32 v7, s[6:7], v6, v6, v51
	v_rcp_f32_e32 v8, v7
	v_div_scale_f32 v9, vcc, v51, v6, v51
	v_fma_f32 v10, -v7, v8, 1.0
	v_fmac_f32_e32 v8, v10, v8
	v_mul_f32_e32 v10, v9, v8
	v_fma_f32 v11, -v7, v10, v9
	v_fmac_f32_e32 v10, v11, v8
	v_fma_f32 v7, -v7, v10, v9
	v_div_fmas_f32 v7, v7, v8, v10
	v_div_fixup_f32 v0, v7, v6, v51
	ds_write_b32 v4, v0 offset:35840
